# K-loops: redundant compiler s_waitcnt lgkmcnt(0) after each barrier removed (asm wait before the barrier already drains LDS reads)
# baseline (speedup 1.0000x reference)
.LBB0_165:
	ds_read_b128 v[114:117], v177
	ds_read_b128 v[118:121], v177 offset:1024
	ds_read_b128 v[122:125], v177 offset:2048
	ds_read_b128 v[126:129], v177 offset:3072
	ds_read_b128 v[182:185], v178
	ds_read_b128 v[186:189], v178 offset:1024
	ds_read_b128 v[190:193], v178 offset:2048
	ds_read_b128 v[194:197], v178 offset:3072
	s_add_u32 s0, s70, 0xfff80080
	s_addc_u32 s1, s71, -1
	s_cmp_eq_u32 s76, 28
	s_cselect_b32 s13, s9, s1
	s_cselect_b32 s12, s61, s0
	s_cselect_b32 s1, s63, s21
	s_cselect_b32 s0, s75, s20
	v_lshl_add_u64 v[174:175], s[70:71], 0, v[166:167]
	s_add_i32 m0, s35, 0xc000
	ds_read_b128 v[198:201], v179
	ds_read_b128 v[202:205], v179 offset:1024
	ds_read_b128 v[206:209], v179 offset:2048
	ds_read_b128 v[210:213], v179 offset:3072
	ds_read_b128 v[214:217], v179 offset:4096
	ds_read_b128 v[218:221], v179 offset:5120
	ds_read_b128 v[222:225], v179 offset:6144
	ds_read_b128 v[226:229], v179 offset:7168
	global_load_lds_dwordx4 v[174:175], off
	v_lshl_add_u64 v[174:175], s[70:71], 0, v[168:169]
	s_add_i32 m0, s35, 0xe000
	s_nop 0
	global_load_lds_dwordx4 v[174:175], off
	s_waitcnt vmcnt(8)
	s_waitcnt lgkmcnt(0)
	s_barrier
	v_mfma_f32_16x16x32_bf16 v[142:145], v[114:117], v[198:201], v[142:145]
	v_mfma_f32_16x16x32_bf16 v[138:141], v[122:125], v[198:201], v[138:141]
	v_mfma_f32_16x16x32_bf16 v[110:113], v[114:117], v[206:209], v[110:113]
	v_mfma_f32_16x16x32_bf16 v[106:109], v[122:125], v[206:209], v[106:109]
	v_mfma_f32_16x16x32_bf16 v[94:97], v[114:117], v[214:217], v[94:97]
	v_mfma_f32_16x16x32_bf16 v[90:93], v[122:125], v[214:217], v[90:93]
	v_mfma_f32_16x16x32_bf16 v[78:81], v[114:117], v[222:225], v[78:81]
	v_mfma_f32_16x16x32_bf16 v[74:77], v[122:125], v[222:225], v[74:77]
	v_mfma_f32_16x16x32_bf16 v[142:145], v[118:121], v[202:205], v[142:145]
	v_mfma_f32_16x16x32_bf16 v[138:141], v[126:129], v[202:205], v[138:141]
	v_mfma_f32_16x16x32_bf16 v[110:113], v[118:121], v[210:213], v[110:113]
	v_mfma_f32_16x16x32_bf16 v[106:109], v[126:129], v[210:213], v[106:109]
	v_mfma_f32_16x16x32_bf16 v[94:97], v[118:121], v[218:221], v[94:97]
	v_mfma_f32_16x16x32_bf16 v[90:93], v[126:129], v[218:221], v[90:93]
	v_mfma_f32_16x16x32_bf16 v[78:81], v[118:121], v[226:229], v[78:81]
	v_mfma_f32_16x16x32_bf16 v[74:77], v[126:129], v[226:229], v[74:77]
	v_mfma_f32_16x16x32_bf16 v[134:137], v[182:185], v[198:201], v[134:137]
	v_mfma_f32_16x16x32_bf16 v[130:133], v[190:193], v[198:201], v[130:133]
	v_mfma_f32_16x16x32_bf16 v[102:105], v[182:185], v[206:209], v[102:105]
	v_mfma_f32_16x16x32_bf16 v[98:101], v[190:193], v[206:209], v[98:101]
	v_mfma_f32_16x16x32_bf16 v[86:89], v[182:185], v[214:217], v[86:89]
	v_mfma_f32_16x16x32_bf16 v[82:85], v[190:193], v[214:217], v[82:85]
	v_mfma_f32_16x16x32_bf16 v[70:73], v[182:185], v[222:225], v[70:73]
	v_mfma_f32_16x16x32_bf16 v[66:69], v[190:193], v[222:225], v[66:69]
	v_mfma_f32_16x16x32_bf16 v[134:137], v[186:189], v[202:205], v[134:137]
	v_mfma_f32_16x16x32_bf16 v[130:133], v[194:197], v[202:205], v[130:133]
	v_mfma_f32_16x16x32_bf16 v[102:105], v[186:189], v[210:213], v[102:105]
	v_mfma_f32_16x16x32_bf16 v[98:101], v[194:197], v[210:213], v[98:101]
	v_mfma_f32_16x16x32_bf16 v[86:89], v[186:189], v[218:221], v[86:89]
	v_mfma_f32_16x16x32_bf16 v[82:85], v[194:197], v[218:221], v[82:85]
	v_mfma_f32_16x16x32_bf16 v[70:73], v[186:189], v[226:229], v[70:73]
	v_mfma_f32_16x16x32_bf16 v[66:69], v[194:197], v[226:229], v[66:69]
	s_barrier
	s_add_i32 s77, s72, s34
	v_lshl_add_u64 v[174:175], s[0:1], 0, v[148:149]
	s_mov_b32 m0, s77
	ds_read_b128 v[198:201], v179 offset:16384
	ds_read_b128 v[202:205], v179 offset:17408
	ds_read_b128 v[206:209], v179 offset:18432
	ds_read_b128 v[210:213], v179 offset:19456
	ds_read_b128 v[214:217], v179 offset:20480
	ds_read_b128 v[218:221], v179 offset:21504
	ds_read_b128 v[222:225], v179 offset:22528
	ds_read_b128 v[226:229], v179 offset:23552
	global_load_lds_dwordx4 v[174:175], off
	s_add_i32 m0, s77, 0x2000
	s_add_u32 s78, s0, 0x20000
	v_lshl_add_u64 v[230:231], s[0:1], 0, v[152:153]
	s_addc_u32 s79, s1, 0
	s_add_i32 s77, s73, s34
	global_load_lds_dwordx4 v[230:231], off
	v_lshl_add_u64 v[232:233], s[78:79], 0, v[148:149]
	s_mov_b32 m0, s77
	v_lshl_add_u64 v[234:235], s[12:13], 0, v[150:151]
	global_load_lds_dwordx4 v[232:233], off
	v_lshl_add_u64 v[232:233], s[78:79], 0, v[152:153]
	s_add_i32 m0, s77, 0x2000
	s_nop 0
	global_load_lds_dwordx4 v[232:233], off
	v_lshl_add_u64 v[232:233], s[12:13], 0, v[146:147]
	s_mov_b32 m0, s35
	s_nop 0
	global_load_lds_dwordx4 v[232:233], off
	s_mov_b32 m0, s36
	s_nop 0
	global_load_lds_dwordx4 v[234:235], off
	s_waitcnt vmcnt(8)
	s_waitcnt lgkmcnt(0)
	s_barrier
	v_mfma_f32_16x16x32_bf16 v[62:65], v[114:117], v[198:201], v[62:65]
	v_mfma_f32_16x16x32_bf16 v[58:61], v[122:125], v[198:201], v[58:61]
	v_mfma_f32_16x16x32_bf16 v[46:49], v[114:117], v[206:209], v[46:49]
	v_mfma_f32_16x16x32_bf16 v[42:45], v[122:125], v[206:209], v[42:45]
	v_mfma_f32_16x16x32_bf16 v[30:33], v[114:117], v[214:217], v[30:33]
	v_mfma_f32_16x16x32_bf16 v[26:29], v[122:125], v[214:217], v[26:29]
	v_mfma_f32_16x16x32_bf16 v[14:17], v[114:117], v[222:225], v[14:17]
	v_mfma_f32_16x16x32_bf16 v[10:13], v[122:125], v[222:225], v[10:13]
	v_mfma_f32_16x16x32_bf16 v[62:65], v[118:121], v[202:205], v[62:65]
	v_mfma_f32_16x16x32_bf16 v[58:61], v[126:129], v[202:205], v[58:61]
	v_mfma_f32_16x16x32_bf16 v[46:49], v[118:121], v[210:213], v[46:49]
	v_mfma_f32_16x16x32_bf16 v[42:45], v[126:129], v[210:213], v[42:45]
	v_mfma_f32_16x16x32_bf16 v[30:33], v[118:121], v[218:221], v[30:33]
	v_mfma_f32_16x16x32_bf16 v[26:29], v[126:129], v[218:221], v[26:29]
	v_mfma_f32_16x16x32_bf16 v[14:17], v[118:121], v[226:229], v[14:17]
	v_mfma_f32_16x16x32_bf16 v[10:13], v[126:129], v[226:229], v[10:13]
	v_mfma_f32_16x16x32_bf16 v[54:57], v[182:185], v[198:201], v[54:57]
	v_mfma_f32_16x16x32_bf16 v[50:53], v[190:193], v[198:201], v[50:53]
	v_mfma_f32_16x16x32_bf16 v[38:41], v[182:185], v[206:209], v[38:41]
	v_mfma_f32_16x16x32_bf16 v[34:37], v[190:193], v[206:209], v[34:37]
	v_mfma_f32_16x16x32_bf16 v[22:25], v[182:185], v[214:217], v[22:25]
	v_mfma_f32_16x16x32_bf16 v[18:21], v[190:193], v[214:217], v[18:21]
	v_mfma_f32_16x16x32_bf16 v[6:9], v[182:185], v[222:225], v[6:9]
	v_mfma_f32_16x16x32_bf16 v[2:5], v[190:193], v[222:225], v[2:5]
	v_mfma_f32_16x16x32_bf16 v[54:57], v[186:189], v[202:205], v[54:57]
	v_mfma_f32_16x16x32_bf16 v[50:53], v[194:197], v[202:205], v[50:53]
	v_mfma_f32_16x16x32_bf16 v[38:41], v[186:189], v[210:213], v[38:41]
	v_mfma_f32_16x16x32_bf16 v[34:37], v[194:197], v[210:213], v[34:37]
	v_mfma_f32_16x16x32_bf16 v[22:25], v[186:189], v[218:221], v[22:25]
	v_mfma_f32_16x16x32_bf16 v[18:21], v[194:197], v[218:221], v[18:21]
	v_mfma_f32_16x16x32_bf16 v[6:9], v[186:189], v[226:229], v[6:9]
	v_mfma_f32_16x16x32_bf16 v[2:5], v[194:197], v[226:229], v[2:5]
	s_barrier
	s_add_i32 s77, 0, 0x18000
	s_add_i32 s78, 0, 0x1c000
	v_add_u32_e32 v126, s77, v159
	v_add_u32_e32 v154, s78, v159
	ds_read_b128 v[114:117], v126
	ds_read_b128 v[118:121], v126 offset:1024
	ds_read_b128 v[122:125], v126 offset:2048
	ds_read_b128 v[126:129], v126 offset:3072
	ds_read_b128 v[182:185], v154
	ds_read_b128 v[186:189], v154 offset:1024
	ds_read_b128 v[190:193], v154 offset:2048
	ds_read_b128 v[194:197], v154 offset:3072
	s_add_u32 s12, s12, 0x80000
	s_addc_u32 s13, s13, 0
	s_mov_b32 m0, s37
	v_lshl_add_u64 v[236:237], s[12:13], 0, v[146:147]
	ds_read_b128 v[198:201], v179 offset:32768
	ds_read_b128 v[202:205], v179 offset:33792
	ds_read_b128 v[206:209], v179 offset:34816
	ds_read_b128 v[210:213], v179 offset:35840
	ds_read_b128 v[214:217], v179 offset:36864
	ds_read_b128 v[218:221], v179 offset:37888
	ds_read_b128 v[222:225], v179 offset:38912
	ds_read_b128 v[226:229], v179 offset:39936
	global_load_lds_dwordx4 v[236:237], off
	v_lshl_add_u64 v[236:237], s[12:13], 0, v[150:151]
	s_mov_b32 m0, s38
	s_nop 0
	global_load_lds_dwordx4 v[236:237], off
	s_waitcnt vmcnt(8)
	s_waitcnt lgkmcnt(0)
	s_barrier
	v_mfma_f32_16x16x32_bf16 v[142:145], v[114:117], v[198:201], v[142:145]
	v_mfma_f32_16x16x32_bf16 v[138:141], v[122:125], v[198:201], v[138:141]
	v_mfma_f32_16x16x32_bf16 v[110:113], v[114:117], v[206:209], v[110:113]
	v_mfma_f32_16x16x32_bf16 v[106:109], v[122:125], v[206:209], v[106:109]
	v_mfma_f32_16x16x32_bf16 v[94:97], v[114:117], v[214:217], v[94:97]
	v_mfma_f32_16x16x32_bf16 v[90:93], v[122:125], v[214:217], v[90:93]
	v_mfma_f32_16x16x32_bf16 v[78:81], v[114:117], v[222:225], v[78:81]
	v_mfma_f32_16x16x32_bf16 v[74:77], v[122:125], v[222:225], v[74:77]
	v_mfma_f32_16x16x32_bf16 v[142:145], v[118:121], v[202:205], v[142:145]
	v_mfma_f32_16x16x32_bf16 v[138:141], v[126:129], v[202:205], v[138:141]
	v_mfma_f32_16x16x32_bf16 v[110:113], v[118:121], v[210:213], v[110:113]
	v_mfma_f32_16x16x32_bf16 v[106:109], v[126:129], v[210:213], v[106:109]
	v_mfma_f32_16x16x32_bf16 v[94:97], v[118:121], v[218:221], v[94:97]
	v_mfma_f32_16x16x32_bf16 v[90:93], v[126:129], v[218:221], v[90:93]
	v_mfma_f32_16x16x32_bf16 v[78:81], v[118:121], v[226:229], v[78:81]
	v_mfma_f32_16x16x32_bf16 v[74:77], v[126:129], v[226:229], v[74:77]
	v_mfma_f32_16x16x32_bf16 v[134:137], v[182:185], v[198:201], v[134:137]
	v_mfma_f32_16x16x32_bf16 v[130:133], v[190:193], v[198:201], v[130:133]
	v_mfma_f32_16x16x32_bf16 v[102:105], v[182:185], v[206:209], v[102:105]
	v_mfma_f32_16x16x32_bf16 v[98:101], v[190:193], v[206:209], v[98:101]
	v_mfma_f32_16x16x32_bf16 v[86:89], v[182:185], v[214:217], v[86:89]
	v_mfma_f32_16x16x32_bf16 v[82:85], v[190:193], v[214:217], v[82:85]
	v_mfma_f32_16x16x32_bf16 v[70:73], v[182:185], v[222:225], v[70:73]
	v_mfma_f32_16x16x32_bf16 v[66:69], v[190:193], v[222:225], v[66:69]
	v_mfma_f32_16x16x32_bf16 v[134:137], v[186:189], v[202:205], v[134:137]
	v_mfma_f32_16x16x32_bf16 v[130:133], v[194:197], v[202:205], v[130:133]
	v_mfma_f32_16x16x32_bf16 v[102:105], v[186:189], v[210:213], v[102:105]
	v_mfma_f32_16x16x32_bf16 v[98:101], v[194:197], v[210:213], v[98:101]
	v_mfma_f32_16x16x32_bf16 v[86:89], v[186:189], v[218:221], v[86:89]
	v_mfma_f32_16x16x32_bf16 v[82:85], v[194:197], v[218:221], v[82:85]
	v_mfma_f32_16x16x32_bf16 v[70:73], v[186:189], v[226:229], v[70:73]
	v_mfma_f32_16x16x32_bf16 v[66:69], v[194:197], v[226:229], v[66:69]
	s_barrier
	s_add_i32 s12, s77, s34
	v_lshl_add_u64 v[174:175], v[174:175], 0, s[52:53]
	s_mov_b32 m0, s12
	ds_read_b128 v[198:201], v179 offset:49152
	ds_read_b128 v[202:205], v179 offset:50176
	ds_read_b128 v[206:209], v179 offset:51200
	ds_read_b128 v[210:213], v179 offset:52224
	ds_read_b128 v[214:217], v179 offset:53248
	ds_read_b128 v[218:221], v179 offset:54272
	ds_read_b128 v[222:225], v179 offset:55296
	ds_read_b128 v[226:229], v179 offset:56320
	global_load_lds_dwordx4 v[174:175], off
	s_add_i32 m0, s12, 0x2000
	s_add_u32 s0, s0, 0x20080
	v_lshl_add_u64 v[174:175], v[230:231], 0, s[52:53]
	s_addc_u32 s1, s1, 0
	s_add_i32 s12, s78, s34
	global_load_lds_dwordx4 v[174:175], off
	v_lshl_add_u64 v[174:175], s[0:1], 0, v[148:149]
	s_mov_b32 m0, s12
	s_nop 0
	global_load_lds_dwordx4 v[174:175], off
	v_lshl_add_u64 v[174:175], s[0:1], 0, v[152:153]
	s_add_i32 m0, s12, 0x2000
	s_nop 0
	global_load_lds_dwordx4 v[174:175], off
	v_lshl_add_u64 v[174:175], v[232:233], 0, s[52:53]
	s_mov_b32 m0, s44
	s_nop 0
	global_load_lds_dwordx4 v[174:175], off
	v_lshl_add_u64 v[174:175], v[234:235], 0, s[52:53]
	s_mov_b32 m0, s45
	s_nop 0
	global_load_lds_dwordx4 v[174:175], off
	s_waitcnt vmcnt(8)
	s_waitcnt lgkmcnt(0)
	s_barrier
	v_mfma_f32_16x16x32_bf16 v[62:65], v[114:117], v[198:201], v[62:65]
	v_mfma_f32_16x16x32_bf16 v[58:61], v[122:125], v[198:201], v[58:61]
	v_mfma_f32_16x16x32_bf16 v[46:49], v[114:117], v[206:209], v[46:49]
	v_mfma_f32_16x16x32_bf16 v[42:45], v[122:125], v[206:209], v[42:45]
	v_mfma_f32_16x16x32_bf16 v[30:33], v[114:117], v[214:217], v[30:33]
	v_mfma_f32_16x16x32_bf16 v[26:29], v[122:125], v[214:217], v[26:29]
	v_mfma_f32_16x16x32_bf16 v[14:17], v[114:117], v[222:225], v[14:17]
	v_mfma_f32_16x16x32_bf16 v[10:13], v[122:125], v[222:225], v[10:13]
	v_mfma_f32_16x16x32_bf16 v[62:65], v[118:121], v[202:205], v[62:65]
	v_mfma_f32_16x16x32_bf16 v[58:61], v[126:129], v[202:205], v[58:61]
	v_mfma_f32_16x16x32_bf16 v[46:49], v[118:121], v[210:213], v[46:49]
	v_mfma_f32_16x16x32_bf16 v[42:45], v[126:129], v[210:213], v[42:45]
	v_mfma_f32_16x16x32_bf16 v[30:33], v[118:121], v[218:221], v[30:33]
	v_mfma_f32_16x16x32_bf16 v[26:29], v[126:129], v[218:221], v[26:29]
	v_mfma_f32_16x16x32_bf16 v[14:17], v[118:121], v[226:229], v[14:17]
	v_mfma_f32_16x16x32_bf16 v[10:13], v[126:129], v[226:229], v[10:13]
	v_mfma_f32_16x16x32_bf16 v[54:57], v[182:185], v[198:201], v[54:57]
	v_mfma_f32_16x16x32_bf16 v[50:53], v[190:193], v[198:201], v[50:53]
	v_mfma_f32_16x16x32_bf16 v[38:41], v[182:185], v[206:209], v[38:41]
	v_mfma_f32_16x16x32_bf16 v[34:37], v[190:193], v[206:209], v[34:37]
	v_mfma_f32_16x16x32_bf16 v[22:25], v[182:185], v[214:217], v[22:25]
	v_mfma_f32_16x16x32_bf16 v[18:21], v[190:193], v[214:217], v[18:21]
	v_mfma_f32_16x16x32_bf16 v[6:9], v[182:185], v[222:225], v[6:9]
	v_mfma_f32_16x16x32_bf16 v[2:5], v[190:193], v[222:225], v[2:5]
	v_mfma_f32_16x16x32_bf16 v[54:57], v[186:189], v[202:205], v[54:57]
	v_mfma_f32_16x16x32_bf16 v[50:53], v[194:197], v[202:205], v[50:53]
	v_mfma_f32_16x16x32_bf16 v[38:41], v[186:189], v[210:213], v[38:41]
	v_mfma_f32_16x16x32_bf16 v[34:37], v[194:197], v[210:213], v[34:37]
	v_mfma_f32_16x16x32_bf16 v[22:25], v[186:189], v[218:221], v[22:25]
	v_mfma_f32_16x16x32_bf16 v[18:21], v[194:197], v[218:221], v[18:21]
	v_mfma_f32_16x16x32_bf16 v[6:9], v[186:189], v[226:229], v[6:9]
	v_mfma_f32_16x16x32_bf16 v[2:5], v[194:197], v[226:229], v[2:5]
	s_barrier
	s_add_i32 s76, s76, 2
	s_add_u32 s70, s70, 0x100
	s_addc_u32 s71, s71, 0
	s_add_u32 s20, s20, 0x100
	s_addc_u32 s21, s21, 0
	s_cmp_gt_u32 s76, 29
	s_cbranch_scc0 .LBB0_165
	s_and_b64 vcc, exec, s[56:57]
	s_cbranch_vccz .LBB0_168
	s_barrier

.LBB0_497:
	ds_read_b128 v[108:111], v215
	ds_read_b128 v[132:135], v215 offset:1024
	ds_read_b128 v[136:139], v215 offset:2048
	ds_read_b128 v[140:143], v215 offset:3072
	ds_read_b128 v[144:147], v220
	ds_read_b128 v[148:151], v220 offset:1024
	ds_read_b128 v[152:155], v220 offset:2048
	ds_read_b128 v[156:159], v220 offset:3072
	s_add_u32 s48, s8, 0xfff80080
	s_addc_u32 s49, s9, -1
	s_cmp_eq_u32 s65, 28
	s_cselect_b32 s51, s63, s49
	s_cselect_b32 s50, s64, s48
	s_cselect_b32 s49, s13, s47
	s_cselect_b32 s48, s12, s46
	v_lshl_add_u64 v[244:245], s[8:9], 0, v[178:179]
	s_add_i32 m0, s11, 0xc000
	ds_read_b128 v[184:187], v216
	ds_read_b128 v[188:191], v216 offset:1024
	ds_read_b128 v[192:195], v216 offset:2048
	ds_read_b128 v[224:227], v216 offset:3072
	ds_read_b128 v[228:231], v216 offset:4096
	ds_read_b128 v[232:235], v216 offset:5120
	ds_read_b128 v[236:239], v216 offset:6144
	ds_read_b128 v[240:243], v216 offset:7168
	global_load_lds_dwordx4 v[244:245], off
	v_lshl_add_u64 v[244:245], s[8:9], 0, v[180:181]
	s_add_i32 m0, s11, 0xe000
	s_nop 0
	global_load_lds_dwordx4 v[244:245], off
	s_waitcnt vmcnt(8)
	s_waitcnt lgkmcnt(0)
	s_barrier
	v_mfma_f32_16x16x32_bf16 v[100:103], v[108:111], v[184:187], v[100:103]
	v_mfma_f32_16x16x32_bf16 v[96:99], v[136:139], v[184:187], v[96:99]
	v_mfma_f32_16x16x32_bf16 v[128:131], v[108:111], v[192:195], v[128:131]
	v_mfma_f32_16x16x32_bf16 v[76:79], v[136:139], v[192:195], v[76:79]
	v_mfma_f32_16x16x32_bf16 v[124:127], v[108:111], v[228:231], v[124:127]
	v_mfma_f32_16x16x32_bf16 v[120:123], v[136:139], v[228:231], v[120:123]
	v_mfma_f32_16x16x32_bf16 v[112:115], v[108:111], v[236:239], v[112:115]
	v_mfma_f32_16x16x32_bf16 v[116:119], v[136:139], v[236:239], v[116:119]
	v_mfma_f32_16x16x32_bf16 v[100:103], v[132:135], v[188:191], v[100:103]
	v_mfma_f32_16x16x32_bf16 v[96:99], v[140:143], v[188:191], v[96:99]
	v_mfma_f32_16x16x32_bf16 v[128:131], v[132:135], v[224:227], v[128:131]
	v_mfma_f32_16x16x32_bf16 v[76:79], v[140:143], v[224:227], v[76:79]
	v_mfma_f32_16x16x32_bf16 v[124:127], v[132:135], v[232:235], v[124:127]
	v_mfma_f32_16x16x32_bf16 v[120:123], v[140:143], v[232:235], v[120:123]
	v_mfma_f32_16x16x32_bf16 v[112:115], v[132:135], v[240:243], v[112:115]
	v_mfma_f32_16x16x32_bf16 v[116:119], v[140:143], v[240:243], v[116:119]
	v_mfma_f32_16x16x32_bf16 v[92:95], v[144:147], v[184:187], v[92:95]
	v_mfma_f32_16x16x32_bf16 v[72:75], v[152:155], v[184:187], v[72:75]
	v_mfma_f32_16x16x32_bf16 v[64:67], v[144:147], v[192:195], v[64:67]
	v_mfma_f32_16x16x32_bf16 v[68:71], v[152:155], v[192:195], v[68:71]
	v_mfma_f32_16x16x32_bf16 v[84:87], v[144:147], v[228:231], v[84:87]
	v_mfma_f32_16x16x32_bf16 v[104:107], v[152:155], v[228:231], v[104:107]
	v_mfma_f32_16x16x32_bf16 v[80:83], v[144:147], v[236:239], v[80:83]
	v_mfma_f32_16x16x32_bf16 v[88:91], v[152:155], v[236:239], v[88:91]
	v_mfma_f32_16x16x32_bf16 v[92:95], v[148:151], v[188:191], v[92:95]
	v_mfma_f32_16x16x32_bf16 v[72:75], v[156:159], v[188:191], v[72:75]
	v_mfma_f32_16x16x32_bf16 v[64:67], v[148:151], v[224:227], v[64:67]
	v_mfma_f32_16x16x32_bf16 v[68:71], v[156:159], v[224:227], v[68:71]
	v_mfma_f32_16x16x32_bf16 v[84:87], v[148:151], v[232:235], v[84:87]
	v_mfma_f32_16x16x32_bf16 v[104:107], v[156:159], v[232:235], v[104:107]
	v_mfma_f32_16x16x32_bf16 v[80:83], v[148:151], v[240:243], v[80:83]
	v_mfma_f32_16x16x32_bf16 v[88:91], v[156:159], v[240:243], v[88:91]
	s_barrier
	s_add_i32 s66, s29, s52
	v_lshl_add_u64 v[244:245], s[48:49], 0, v[162:163]
	s_mov_b32 m0, s66
	ds_read_b128 v[184:187], v216 offset:16384
	ds_read_b128 v[188:191], v216 offset:17408
	ds_read_b128 v[192:195], v216 offset:18432
	ds_read_b128 v[224:227], v216 offset:19456
	ds_read_b128 v[228:231], v216 offset:20480
	ds_read_b128 v[232:235], v216 offset:21504
	ds_read_b128 v[236:239], v216 offset:22528
	ds_read_b128 v[240:243], v216 offset:23552
	global_load_lds_dwordx4 v[244:245], off
	s_add_i32 m0, s66, 0x2000
	s_add_u32 s66, s48, 0x20000
	v_lshl_add_u64 v[246:247], s[48:49], 0, v[166:167]
	s_addc_u32 s67, s49, 0
	s_add_i32 s68, s59, s52
	global_load_lds_dwordx4 v[246:247], off
	v_lshl_add_u64 v[248:249], s[66:67], 0, v[162:163]
	s_mov_b32 m0, s68
	v_lshl_add_u64 v[250:251], s[50:51], 0, v[164:165]
	global_load_lds_dwordx4 v[248:249], off
	v_lshl_add_u64 v[248:249], s[66:67], 0, v[166:167]
	s_add_i32 m0, s68, 0x2000
	s_nop 0
	global_load_lds_dwordx4 v[248:249], off
	v_lshl_add_u64 v[248:249], s[50:51], 0, v[160:161]
	s_mov_b32 m0, s11
	s_nop 0
	global_load_lds_dwordx4 v[248:249], off
	s_mov_b32 m0, s33
	s_nop 0
	global_load_lds_dwordx4 v[250:251], off
	s_waitcnt vmcnt(8)
	s_waitcnt lgkmcnt(0)
	s_barrier
	v_mfma_f32_16x16x32_bf16 v[12:15], v[108:111], v[184:187], v[12:15]
	v_mfma_f32_16x16x32_bf16 v[20:23], v[136:139], v[184:187], v[20:23]
	v_mfma_f32_16x16x32_bf16 v[24:27], v[108:111], v[192:195], v[24:27]
	v_mfma_f32_16x16x32_bf16 v[28:31], v[136:139], v[192:195], v[28:31]
	v_mfma_f32_16x16x32_bf16 v[40:43], v[108:111], v[228:231], v[40:43]
	v_mfma_f32_16x16x32_bf16 v[44:47], v[136:139], v[228:231], v[44:47]
	v_mfma_f32_16x16x32_bf16 v[48:51], v[108:111], v[236:239], v[48:51]
	v_mfma_f32_16x16x32_bf16 v[52:55], v[136:139], v[236:239], v[52:55]
	v_mfma_f32_16x16x32_bf16 v[12:15], v[132:135], v[188:191], v[12:15]
	v_mfma_f32_16x16x32_bf16 v[20:23], v[140:143], v[188:191], v[20:23]
	v_mfma_f32_16x16x32_bf16 v[24:27], v[132:135], v[224:227], v[24:27]
	v_mfma_f32_16x16x32_bf16 v[28:31], v[140:143], v[224:227], v[28:31]
	v_mfma_f32_16x16x32_bf16 v[40:43], v[132:135], v[232:235], v[40:43]
	v_mfma_f32_16x16x32_bf16 v[44:47], v[140:143], v[232:235], v[44:47]
	v_mfma_f32_16x16x32_bf16 v[48:51], v[132:135], v[240:243], v[48:51]
	v_mfma_f32_16x16x32_bf16 v[52:55], v[140:143], v[240:243], v[52:55]
	v_mfma_f32_16x16x32_bf16 v[0:3], v[144:147], v[184:187], v[0:3]
	v_mfma_f32_16x16x32_bf16 v[4:7], v[152:155], v[184:187], v[4:7]
	v_mfma_f32_16x16x32_bf16 v[8:11], v[144:147], v[192:195], v[8:11]
	v_mfma_f32_16x16x32_bf16 v[16:19], v[152:155], v[192:195], v[16:19]
	v_mfma_f32_16x16x32_bf16 v[32:35], v[144:147], v[228:231], v[32:35]
	v_mfma_f32_16x16x32_bf16 v[36:39], v[152:155], v[228:231], v[36:39]
	v_mfma_f32_16x16x32_bf16 v[56:59], v[144:147], v[236:239], v[56:59]
	v_mfma_f32_16x16x32_bf16 v[60:63], v[152:155], v[236:239], v[60:63]
	v_mfma_f32_16x16x32_bf16 v[0:3], v[148:151], v[188:191], v[0:3]
	v_mfma_f32_16x16x32_bf16 v[4:7], v[156:159], v[188:191], v[4:7]
	v_mfma_f32_16x16x32_bf16 v[8:11], v[148:151], v[224:227], v[8:11]
	v_mfma_f32_16x16x32_bf16 v[16:19], v[156:159], v[224:227], v[16:19]
	v_mfma_f32_16x16x32_bf16 v[32:35], v[148:151], v[232:235], v[32:35]
	v_mfma_f32_16x16x32_bf16 v[36:39], v[156:159], v[232:235], v[36:39]
	v_mfma_f32_16x16x32_bf16 v[56:59], v[148:151], v[240:243], v[56:59]
	v_mfma_f32_16x16x32_bf16 v[60:63], v[156:159], v[240:243], v[60:63]
	s_barrier
	s_add_i32 s66, 0, 0x18000
	s_add_i32 s67, 0, 0x1c000
	v_add_u32_e32 v140, s66, v197
	v_add_u32_e32 v156, s67, v197
	ds_read_b128 v[108:111], v140
	ds_read_b128 v[132:135], v140 offset:1024
	ds_read_b128 v[136:139], v140 offset:2048
	ds_read_b128 v[140:143], v140 offset:3072
	ds_read_b128 v[144:147], v156
	ds_read_b128 v[148:151], v156 offset:1024
	ds_read_b128 v[152:155], v156 offset:2048
	ds_read_b128 v[156:159], v156 offset:3072
	s_add_u32 s50, s50, 0x80000
	s_addc_u32 s51, s51, 0
	s_mov_b32 m0, s53
	v_lshl_add_u64 v[252:253], s[50:51], 0, v[160:161]
	ds_read_b128 v[184:187], v216 offset:32768
	ds_read_b128 v[188:191], v216 offset:33792
	ds_read_b128 v[192:195], v216 offset:34816
	ds_read_b128 v[224:227], v216 offset:35840
	ds_read_b128 v[228:231], v216 offset:36864
	ds_read_b128 v[232:235], v216 offset:37888
	ds_read_b128 v[236:239], v216 offset:38912
	ds_read_b128 v[240:243], v216 offset:39936
	global_load_lds_dwordx4 v[252:253], off
	v_lshl_add_u64 v[252:253], s[50:51], 0, v[164:165]
	s_mov_b32 m0, s54
	s_nop 0
	global_load_lds_dwordx4 v[252:253], off
	s_waitcnt vmcnt(8)
	s_waitcnt lgkmcnt(0)
	s_barrier
	v_mfma_f32_16x16x32_bf16 v[100:103], v[108:111], v[184:187], v[100:103]
	v_mfma_f32_16x16x32_bf16 v[96:99], v[136:139], v[184:187], v[96:99]
	v_mfma_f32_16x16x32_bf16 v[128:131], v[108:111], v[192:195], v[128:131]
	v_mfma_f32_16x16x32_bf16 v[76:79], v[136:139], v[192:195], v[76:79]
	v_mfma_f32_16x16x32_bf16 v[124:127], v[108:111], v[228:231], v[124:127]
	v_mfma_f32_16x16x32_bf16 v[120:123], v[136:139], v[228:231], v[120:123]
	v_mfma_f32_16x16x32_bf16 v[112:115], v[108:111], v[236:239], v[112:115]
	v_mfma_f32_16x16x32_bf16 v[116:119], v[136:139], v[236:239], v[116:119]
	v_mfma_f32_16x16x32_bf16 v[100:103], v[132:135], v[188:191], v[100:103]
	v_mfma_f32_16x16x32_bf16 v[96:99], v[140:143], v[188:191], v[96:99]
	v_mfma_f32_16x16x32_bf16 v[128:131], v[132:135], v[224:227], v[128:131]
	v_mfma_f32_16x16x32_bf16 v[76:79], v[140:143], v[224:227], v[76:79]
	v_mfma_f32_16x16x32_bf16 v[124:127], v[132:135], v[232:235], v[124:127]
	v_mfma_f32_16x16x32_bf16 v[120:123], v[140:143], v[232:235], v[120:123]
	v_mfma_f32_16x16x32_bf16 v[112:115], v[132:135], v[240:243], v[112:115]
	v_mfma_f32_16x16x32_bf16 v[116:119], v[140:143], v[240:243], v[116:119]
	v_mfma_f32_16x16x32_bf16 v[92:95], v[144:147], v[184:187], v[92:95]
	v_mfma_f32_16x16x32_bf16 v[72:75], v[152:155], v[184:187], v[72:75]
	v_mfma_f32_16x16x32_bf16 v[64:67], v[144:147], v[192:195], v[64:67]
	v_mfma_f32_16x16x32_bf16 v[68:71], v[152:155], v[192:195], v[68:71]
	v_mfma_f32_16x16x32_bf16 v[84:87], v[144:147], v[228:231], v[84:87]
	v_mfma_f32_16x16x32_bf16 v[104:107], v[152:155], v[228:231], v[104:107]
	v_mfma_f32_16x16x32_bf16 v[80:83], v[144:147], v[236:239], v[80:83]
	v_mfma_f32_16x16x32_bf16 v[88:91], v[152:155], v[236:239], v[88:91]
	v_mfma_f32_16x16x32_bf16 v[92:95], v[148:151], v[188:191], v[92:95]
	v_mfma_f32_16x16x32_bf16 v[72:75], v[156:159], v[188:191], v[72:75]
	v_mfma_f32_16x16x32_bf16 v[64:67], v[148:151], v[224:227], v[64:67]
	v_mfma_f32_16x16x32_bf16 v[68:71], v[156:159], v[224:227], v[68:71]
	v_mfma_f32_16x16x32_bf16 v[84:87], v[148:151], v[232:235], v[84:87]
	v_mfma_f32_16x16x32_bf16 v[104:107], v[156:159], v[232:235], v[104:107]
	v_mfma_f32_16x16x32_bf16 v[80:83], v[148:151], v[240:243], v[80:83]
	v_mfma_f32_16x16x32_bf16 v[88:91], v[156:159], v[240:243], v[88:91]
	s_barrier
	s_add_i32 s50, s66, s52
	v_lshl_add_u64 v[244:245], v[244:245], 0, s[24:25]
	s_mov_b32 m0, s50
	ds_read_b128 v[184:187], v216 offset:49152
	ds_read_b128 v[188:191], v216 offset:50176
	ds_read_b128 v[192:195], v216 offset:51200
	ds_read_b128 v[224:227], v216 offset:52224
	ds_read_b128 v[228:231], v216 offset:53248
	ds_read_b128 v[232:235], v216 offset:54272
	ds_read_b128 v[236:239], v216 offset:55296
	ds_read_b128 v[240:243], v216 offset:56320
	global_load_lds_dwordx4 v[244:245], off
	s_add_i32 m0, s50, 0x2000
	s_add_u32 s48, s48, 0x20080
	v_lshl_add_u64 v[244:245], v[246:247], 0, s[24:25]
	s_addc_u32 s49, s49, 0
	s_add_i32 s50, s67, s52
	global_load_lds_dwordx4 v[244:245], off
	v_lshl_add_u64 v[244:245], s[48:49], 0, v[162:163]
	s_mov_b32 m0, s50
	s_nop 0
	global_load_lds_dwordx4 v[244:245], off
	v_lshl_add_u64 v[244:245], s[48:49], 0, v[166:167]
	s_add_i32 m0, s50, 0x2000
	s_nop 0
	global_load_lds_dwordx4 v[244:245], off
	v_lshl_add_u64 v[244:245], v[248:249], 0, s[24:25]
	s_mov_b32 m0, s57
	s_nop 0
	global_load_lds_dwordx4 v[244:245], off
	v_lshl_add_u64 v[244:245], v[250:251], 0, s[24:25]
	s_mov_b32 m0, s58
	s_nop 0
	global_load_lds_dwordx4 v[244:245], off
	s_waitcnt vmcnt(8)
	s_waitcnt lgkmcnt(0)
	s_barrier
	v_mfma_f32_16x16x32_bf16 v[12:15], v[108:111], v[184:187], v[12:15]
	v_mfma_f32_16x16x32_bf16 v[20:23], v[136:139], v[184:187], v[20:23]
	v_mfma_f32_16x16x32_bf16 v[24:27], v[108:111], v[192:195], v[24:27]
	v_mfma_f32_16x16x32_bf16 v[28:31], v[136:139], v[192:195], v[28:31]
	v_mfma_f32_16x16x32_bf16 v[40:43], v[108:111], v[228:231], v[40:43]
	v_mfma_f32_16x16x32_bf16 v[44:47], v[136:139], v[228:231], v[44:47]
	v_mfma_f32_16x16x32_bf16 v[48:51], v[108:111], v[236:239], v[48:51]
	v_mfma_f32_16x16x32_bf16 v[52:55], v[136:139], v[236:239], v[52:55]
	v_mfma_f32_16x16x32_bf16 v[12:15], v[132:135], v[188:191], v[12:15]
	v_mfma_f32_16x16x32_bf16 v[20:23], v[140:143], v[188:191], v[20:23]
	v_mfma_f32_16x16x32_bf16 v[24:27], v[132:135], v[224:227], v[24:27]
	v_mfma_f32_16x16x32_bf16 v[28:31], v[140:143], v[224:227], v[28:31]
	v_mfma_f32_16x16x32_bf16 v[40:43], v[132:135], v[232:235], v[40:43]
	v_mfma_f32_16x16x32_bf16 v[44:47], v[140:143], v[232:235], v[44:47]
	v_mfma_f32_16x16x32_bf16 v[48:51], v[132:135], v[240:243], v[48:51]
	v_mfma_f32_16x16x32_bf16 v[52:55], v[140:143], v[240:243], v[52:55]
	v_mfma_f32_16x16x32_bf16 v[0:3], v[144:147], v[184:187], v[0:3]
	v_mfma_f32_16x16x32_bf16 v[4:7], v[152:155], v[184:187], v[4:7]
	v_mfma_f32_16x16x32_bf16 v[8:11], v[144:147], v[192:195], v[8:11]
	v_mfma_f32_16x16x32_bf16 v[16:19], v[152:155], v[192:195], v[16:19]
	v_mfma_f32_16x16x32_bf16 v[32:35], v[144:147], v[228:231], v[32:35]
	v_mfma_f32_16x16x32_bf16 v[36:39], v[152:155], v[228:231], v[36:39]
	v_mfma_f32_16x16x32_bf16 v[56:59], v[144:147], v[236:239], v[56:59]
	v_mfma_f32_16x16x32_bf16 v[60:63], v[152:155], v[236:239], v[60:63]
	v_mfma_f32_16x16x32_bf16 v[0:3], v[148:151], v[188:191], v[0:3]
	v_mfma_f32_16x16x32_bf16 v[4:7], v[156:159], v[188:191], v[4:7]
	v_mfma_f32_16x16x32_bf16 v[8:11], v[148:151], v[224:227], v[8:11]
	v_mfma_f32_16x16x32_bf16 v[16:19], v[156:159], v[224:227], v[16:19]
	v_mfma_f32_16x16x32_bf16 v[32:35], v[148:151], v[232:235], v[32:35]
	v_mfma_f32_16x16x32_bf16 v[36:39], v[156:159], v[232:235], v[36:39]
	v_mfma_f32_16x16x32_bf16 v[56:59], v[148:151], v[240:243], v[56:59]
	v_mfma_f32_16x16x32_bf16 v[60:63], v[156:159], v[240:243], v[60:63]
	s_barrier
	s_add_i32 s65, s65, 2
	s_add_u32 s8, s8, 0x100
	s_addc_u32 s9, s9, 0
	s_add_u32 s46, s46, 0x100
	s_addc_u32 s47, s47, 0
	s_cmp_gt_u32 s65, 29
	s_cbranch_scc0 .LBB0_497
	s_and_b64 vcc, exec, s[36:37]
	s_cbranch_vccz .LBB0_500
	s_barrier
